# attn_a ping-pong: two staging sets (prefetch 2 tiles ahead), x2 unroll with static LDS buffer offsets, reads before ds_writes in X
# speedup vs baseline: 1.0236x; 1.0038x over previous
; #define LAS __attribute__((address_space(3)))
; template <int DQK, int KA8, int DV, bool BIAS, bool JOINT>
; DI void attn_core(LAS unsigned char* lds, const bf16_t* Qrow, const bf16_t* KpA, int ldkA, const bf16_t* KpB, int ldkB, const bf16_t* Vp, int ldv,
;                   int qb, int wid, int lane, const float* qng  , f32x16 (&O)[DV / 32]) {
;     ...
;     auto gload = [&](int kt) {
; #pragma unroll
;         for (int i = 0; i < NL; ++i) { const int c = tid + i * 512;
;             if (i * 512 < NKC) { const int row = c / KC, cc = c % KC;
;                 const bf16_t* src = (cc < KA8) ? KpA + (size_t)(kt * 64 + row) * ldkA + cc * 8 : KpB + (size_t)(kt * 64 + row) * ldkB + (cc - KA8) * 8;
;                 stg[i] = *(const u32x4*)src; }
;             else { const int c2 = c - NKC, row = c2 / VC, cc = c2 % VC; stg[i] = *(const u32x4*)(Vp + (size_t)(kt * 64 + row) * ldv + cc * 8); } }
;     };
;     auto lstore = [&](int buf) {
; #pragma unroll
;         for (int i = 0; i < NL; ++i) { const int c = tid + i * 512;
;             if (i * 512 < NKC) { const int row = c / KC, cc = c % KC; *(LAS u32x4*)(lds + buf * STG + row * KROW + cc * 16) = stg[i]; }
;             else { const int c2 = c - NKC, row = c2 / VC, cc = c2 % VC; *(LAS u32x4*)(lds + buf * STG + 64 * KROW + row * VROW + cc * 16) = stg[i]; } }
;     };
;     gload(0); lstore(0); __syncthreads();
.Laa_pass:
	s_barrier
	s_lshl_b32 s58, s41, 7
	s_add_u32 s30, s48, s58
	s_addc_u32 s31, s49, 0
	s_add_u32 s56, s46, s58
	s_addc_u32 s57, s47, 0
	global_load_dwordx4 v[128:131], v176, s[30:31]
	global_load_dwordx4 v[112:115], v197, s[56:57] offset:0
	global_load_dwordx4 v[116:119], v197, s[56:57] offset:32
	global_load_dwordx4 v[120:123], v197, s[56:57] offset:64
	global_load_dwordx4 v[124:127], v197, s[56:57] offset:96
	s_add_u32 s30, s30, 0x100000
	s_addc_u32 s31, s31, 0
	s_mov_b64 s[34:35], s[50:51]
	v_mov_b32_e32 v0, 0
	v_mov_b32_e32 v1, 0
	v_mov_b32_e32 v2, 0
	v_mov_b32_e32 v3, 0
	v_mov_b32_e32 v4, 0
	v_mov_b32_e32 v5, 0
	v_mov_b32_e32 v6, 0
	v_mov_b32_e32 v7, 0
	v_mov_b32_e32 v8, 0
	v_mov_b32_e32 v9, 0
	v_mov_b32_e32 v10, 0
	v_mov_b32_e32 v11, 0
	v_mov_b32_e32 v12, 0
	v_mov_b32_e32 v13, 0
	v_mov_b32_e32 v14, 0
	v_mov_b32_e32 v15, 0
	v_mov_b32_e32 v16, 0
	v_mov_b32_e32 v17, 0
	v_mov_b32_e32 v18, 0
	v_mov_b32_e32 v19, 0
	v_mov_b32_e32 v20, 0
	v_mov_b32_e32 v21, 0
	v_mov_b32_e32 v22, 0
	v_mov_b32_e32 v23, 0
	v_mov_b32_e32 v24, 0
	v_mov_b32_e32 v25, 0
	v_mov_b32_e32 v26, 0
	v_mov_b32_e32 v27, 0
	v_mov_b32_e32 v28, 0
	v_mov_b32_e32 v29, 0
	v_mov_b32_e32 v30, 0
	v_mov_b32_e32 v31, 0
	v_mov_b32_e32 v32, 0
	v_mov_b32_e32 v33, 0
	v_mov_b32_e32 v34, 0
	v_mov_b32_e32 v35, 0
	v_mov_b32_e32 v36, 0
	v_mov_b32_e32 v37, 0
	v_mov_b32_e32 v38, 0
	v_mov_b32_e32 v39, 0
	v_mov_b32_e32 v40, 0
	v_mov_b32_e32 v41, 0
	v_mov_b32_e32 v42, 0
	v_mov_b32_e32 v43, 0
	v_mov_b32_e32 v44, 0
	v_mov_b32_e32 v45, 0
	v_mov_b32_e32 v46, 0
	v_mov_b32_e32 v47, 0
	v_mov_b32_e32 v48, 0
	v_mov_b32_e32 v49, 0
	v_mov_b32_e32 v50, 0
	v_mov_b32_e32 v51, 0
	v_mov_b32_e32 v52, 0
	v_mov_b32_e32 v53, 0
	v_mov_b32_e32 v54, 0
	v_mov_b32_e32 v55, 0
	v_mov_b32_e32 v56, 0
	v_mov_b32_e32 v57, 0
	v_mov_b32_e32 v58, 0
	v_mov_b32_e32 v59, 0
	v_mov_b32_e32 v60, 0
	v_mov_b32_e32 v61, 0
	v_mov_b32_e32 v62, 0
	v_mov_b32_e32 v63, 0
	v_mov_b32_e32 v183, 0
	v_mov_b32_e32 v184, 0
	s_mov_b32 s40, 0
	s_waitcnt vmcnt(4)
	ds_write_b128 v174, v[128:131]
	s_waitcnt lgkmcnt(0)
	global_load_dwordx4 v[128:131], v176, s[30:31]
	global_load_dwordx4 v[132:135], v177, s[34:35]
	global_load_dwordx4 v[136:139], v182, s[34:35]
	s_add_u32 s30, s30, 0x100000
	s_addc_u32 s31, s31, 0
	s_add_u32 s34, s34, 0x100000
	s_addc_u32 s35, s35, 0
	global_load_dwordx4 v[204:207], v176, s[30:31]
	global_load_dwordx4 v[208:211], v177, s[34:35]
	global_load_dwordx4 v[212:215], v182, s[34:35]
	s_add_u32 s30, s30, 0x100000
	s_addc_u32 s31, s31, 0
	s_add_u32 s34, s34, 0x100000
	s_addc_u32 s35, s35, 0
	s_barrier
	s_cmp_lt_u32 s26, 4
	s_cbranch_scc1 .Laa_nostag
	s_barrier

; template <int DQK, int KA8, int DV, bool BIAS, bool JOINT>
; DI void attn_core(LAS unsigned char* lds, const bf16_t* Qrow, const bf16_t* KpA, int ldkA, const bf16_t* KpB, int ldkB, const bf16_t* Vp, int ldv,
;                   int qb, int wid, int lane, const float* qng  , f32x16 (&O)[DV / 32]) {
;     ...
;     for (int kt = 0; kt < nkt; ++kt) {
;         if (kt + 1 < nkt) gload(kt + 1);
;         if (JOINT && kt <= myc) {
;             LAS unsigned char* kb = lds + (kt & 1) * STG; LAS unsigned char* vb = kb + 64 * KROW;
;             const bool far = (kt * 64 + 63 - q0w <= -91);
;             f32x16 S0, S1;
; #pragma unroll
;             for (int i = 0; i < 16; ++i) { S0[i] = 0.f; S1[i] = 0.f; }
; #pragma unroll
;             for (int s = 0; s < DQK / 16; ++s) {
;                 const bf16x8 k0 = *(LAS const bf16x8*)(kb + koff + 32 * s), k1 = *(LAS const bf16x8*)(kb + koff + 32 * KROW + 32 * s);
;                 S0 = mfma32(k0, qf[s], S0); S1 = mfma32(k1, qf[s], S1);
;             }
;             if (BIAS && !far) {
;                 const int rb = kt * 64 - (q0w + l32) + 128;
; #pragma unroll
;                 for (int i = 0; i < 16; ++i) { const int i0 = rb + crow(i, hh); S0[i] += btab[i0 < 0 ? 0 : i0]; S1[i] += btab[i0 + 32 < 0 ? 0 : i0 + 32]; }
;             }
;             if (mnz) {
; #pragma unroll
;                 for (int i = 0; i < 16; ++i) { S0[i] -= m; S1[i] -= m; }
;             }
;             float mx = fmaxf(S0[0], S1[0]);
; #pragma unroll
;             for (int i = 1; i < 16; ++i) mx = fmaxf(mx, fmaxf(S0[i], S1[i]));
;             mx = fmaxf(mx, __shfl_xor(mx, 32));
;             if (__any(mx > 64.f || (kt == 0 && mx < -64.f))) {
;                 const float dm = (mx > 64.f || (kt == 0 && mx < -64.f)) ? mx : 0.f, alpha = __builtin_amdgcn_exp2f(-dm); m += dm; mnz = true;
;                 l *= alpha;
; #pragma unroll
;                 for (int dt = 0; dt < DV / 32; ++dt) O[dt] *= alpha;
; #pragma unroll
;                 for (int i = 0; i < 16; ++i) { S0[i] -= dm; S1[i] -= dm; }
;             }
;             float ps = 0.f;
; #pragma unroll
;             for (int i = 0; i < 16; ++i) { S0[i] = __builtin_amdgcn_exp2f(S0[i]); S1[i] = __builtin_amdgcn_exp2f(S1[i]); ps += S0[i] + S1[i]; }
;             l += ps;
; #pragma unroll
;             for (int half = 0; half < 2; ++half)
; #pragma unroll
;                 for (int s = 0; s < 2; ++s) {
.Laa_loop:
	s_add_i32 s58, s25, 1
	s_cmp_eq_u32 s24, 0
	s_cbranch_scc1 .Laa_x0_qk
	s_cmp_gt_u32 s24, s58
	s_cbranch_scc1 .Laa_x0_none
	s_cmp_eq_u32 s24, s58
	s_cbranch_scc1 .Laa_x0_pv
	ds_read_b64_tr_b16 v[140:141], v173 offset:38912
	ds_read_b64_tr_b16 v[142:143], v173 offset:41472
	ds_read_b64_tr_b16 v[144:145], v173 offset:38976
	ds_read_b64_tr_b16 v[146:147], v173 offset:41536
	ds_read_b64_tr_b16 v[148:149], v173 offset:39040
	ds_read_b64_tr_b16 v[150:151], v173 offset:41600
	ds_read_b64_tr_b16 v[152:153], v173 offset:39104
	ds_read_b64_tr_b16 v[154:155], v173 offset:41664
	ds_read_b64_tr_b16 v[156:157], v173 offset:44032
	ds_read_b64_tr_b16 v[158:159], v173 offset:46592
	ds_read_b64_tr_b16 v[160:161], v173 offset:44096
	ds_read_b64_tr_b16 v[162:163], v173 offset:46656
	s_waitcnt lgkmcnt(10)
	v_mfma_f32_32x32x16_bf16 v[0:15], v[140:143], v[96:99], v[0:15]
	ds_read_b64_tr_b16 v[164:165], v173 offset:44160
	ds_read_b64_tr_b16 v[166:167], v173 offset:46720
	s_waitcnt lgkmcnt(10)
	v_mfma_f32_32x32x16_bf16 v[16:31], v[144:147], v[96:99], v[16:31]
	s_add_i32 s58, s24, 2
	s_cmp_lt_u32 s58, s17
	s_cbranch_scc1 .Laa_h3_1
	s_waitcnt vmcnt(2)
	s_branch .Laa_hk_2
.Laa_h3_1:
	s_waitcnt vmcnt(3)
.Laa_hk_2:
	ds_write_b128 v174, v[128:131] offset:9216
.Laa_hv_3:
	ds_write_b128 v175, v[132:135] offset:18432
	ds_write_b128 v175, v[136:139] offset:28672
	ds_read_b64_tr_b16 v[168:169], v173 offset:44224
	ds_read_b64_tr_b16 v[170:171], v173 offset:46784
	s_waitcnt lgkmcnt(12)
	v_mfma_f32_32x32x16_bf16 v[32:47], v[148:151], v[96:99], v[32:47]
	ds_read_b64_tr_b16 v[140:141], v173 offset:49152
	ds_read_b64_tr_b16 v[142:143], v173 offset:51712
	s_waitcnt lgkmcnt(12)
	v_mfma_f32_32x32x16_bf16 v[48:63], v[152:155], v[96:99], v[48:63]
	ds_read_b64_tr_b16 v[144:145], v173 offset:49216
	ds_read_b64_tr_b16 v[146:147], v173 offset:51776
	s_waitcnt lgkmcnt(12)
	v_mfma_f32_32x32x16_bf16 v[0:15], v[156:159], v[100:103], v[0:15]
	ds_read_b64_tr_b16 v[148:149], v173 offset:49280
	ds_read_b64_tr_b16 v[150:151], v173 offset:51840
	s_waitcnt lgkmcnt(12)
	v_mfma_f32_32x32x16_bf16 v[16:31], v[160:163], v[100:103], v[16:31]
	ds_read_b64_tr_b16 v[152:153], v173 offset:49344
	ds_read_b64_tr_b16 v[154:155], v173 offset:51904
	s_waitcnt lgkmcnt(12)
	v_mfma_f32_32x32x16_bf16 v[32:47], v[164:167], v[100:103], v[32:47]
	ds_read_b64_tr_b16 v[156:157], v173 offset:54272
	ds_read_b64_tr_b16 v[158:159], v173 offset:56832
	s_waitcnt lgkmcnt(10)
	v_mfma_f32_32x32x16_bf16 v[48:63], v[168:171], v[100:103], v[48:63]
	ds_read_b64_tr_b16 v[160:161], v173 offset:54336
	ds_read_b64_tr_b16 v[162:163], v173 offset:56896
	s_waitcnt lgkmcnt(10)
	v_mfma_f32_32x32x16_bf16 v[0:15], v[140:143], v[104:107], v[0:15]
	ds_read_b64_tr_b16 v[164:165], v173 offset:54400
	ds_read_b64_tr_b16 v[166:167], v173 offset:56960
	s_waitcnt lgkmcnt(10)
	v_mfma_f32_32x32x16_bf16 v[16:31], v[144:147], v[104:107], v[16:31]
	ds_read_b64_tr_b16 v[168:169], v173 offset:54464
	ds_read_b64_tr_b16 v[170:171], v173 offset:57024
	s_waitcnt lgkmcnt(10)
	v_mfma_f32_32x32x16_bf16 v[32:47], v[148:151], v[104:107], v[32:47]
	ds_read_b128 v[140:143], v172 offset:0
	s_waitcnt lgkmcnt(9)
	v_mfma_f32_32x32x16_bf16 v[48:63], v[152:155], v[104:107], v[48:63]
	ds_read_b128 v[144:147], v172 offset:4608
	s_waitcnt lgkmcnt(8)
	v_mfma_f32_32x32x16_bf16 v[0:15], v[156:159], v[108:111], v[0:15]
	ds_read_b128 v[148:151], v172 offset:32
	s_waitcnt lgkmcnt(7)
	v_mfma_f32_32x32x16_bf16 v[16:31], v[160:163], v[108:111], v[16:31]
	ds_read_b128 v[152:155], v172 offset:4640
	s_waitcnt lgkmcnt(6)
	v_mfma_f32_32x32x16_bf16 v[32:47], v[164:167], v[108:111], v[32:47]
	ds_read_b128 v[156:159], v172 offset:64
	s_waitcnt lgkmcnt(5)
	v_mfma_f32_32x32x16_bf16 v[48:63], v[168:171], v[108:111], v[48:63]
	ds_read_b128 v[160:163], v172 offset:4672
	s_waitcnt lgkmcnt(5)
	v_mfma_f32_32x32x16_bf16 v[64:79], v[140:143], v[112:115], 0
	ds_read_b128 v[164:167], v172 offset:96
	s_waitcnt lgkmcnt(5)
	v_mfma_f32_32x32x16_bf16 v[80:95], v[144:147], v[112:115], 0
	ds_read_b128 v[168:171], v172 offset:4704
	s_waitcnt lgkmcnt(5)
	v_mfma_f32_32x32x16_bf16 v[64:79], v[148:151], v[116:119], v[64:79]
	s_waitcnt lgkmcnt(4)
	v_mfma_f32_32x32x16_bf16 v[80:95], v[152:155], v[116:119], v[80:95]
	s_waitcnt lgkmcnt(3)
	v_mfma_f32_32x32x16_bf16 v[64:79], v[156:159], v[120:123], v[64:79]
	s_waitcnt lgkmcnt(2)
	v_mfma_f32_32x32x16_bf16 v[80:95], v[160:163], v[120:123], v[80:95]
	s_waitcnt lgkmcnt(1)
	v_mfma_f32_32x32x16_bf16 v[64:79], v[164:167], v[124:127], v[64:79]
	s_waitcnt lgkmcnt(0)
	v_mfma_f32_32x32x16_bf16 v[80:95], v[168:171], v[124:127], v[80:95]
	s_branch .Laa_x0_end
.Laa_x0_pv:
	ds_read_b64_tr_b16 v[140:141], v173 offset:38912
	ds_read_b64_tr_b16 v[142:143], v173 offset:41472
	ds_read_b64_tr_b16 v[144:145], v173 offset:38976
	ds_read_b64_tr_b16 v[146:147], v173 offset:41536
	ds_read_b64_tr_b16 v[148:149], v173 offset:39040
	ds_read_b64_tr_b16 v[150:151], v173 offset:41600
	ds_read_b64_tr_b16 v[152:153], v173 offset:39104
	ds_read_b64_tr_b16 v[154:155], v173 offset:41664
	ds_read_b64_tr_b16 v[156:157], v173 offset:44032
	ds_read_b64_tr_b16 v[158:159], v173 offset:46592
	ds_read_b64_tr_b16 v[160:161], v173 offset:44096
	ds_read_b64_tr_b16 v[162:163], v173 offset:46656
	s_waitcnt lgkmcnt(10)
	v_mfma_f32_32x32x16_bf16 v[0:15], v[140:143], v[96:99], v[0:15]
	ds_read_b64_tr_b16 v[164:165], v173 offset:44160
	ds_read_b64_tr_b16 v[166:167], v173 offset:46720
	s_waitcnt lgkmcnt(10)
	v_mfma_f32_32x32x16_bf16 v[16:31], v[144:147], v[96:99], v[16:31]
	s_add_i32 s58, s24, 2
	s_cmp_lt_u32 s58, s17
	s_cbranch_scc1 .Laa_h3_4
	s_waitcnt vmcnt(2)
	s_branch .Laa_hk_5

; #define LAS __attribute__((address_space(3)))
; DI unsigned pk2(float a, float b) { f32x2 v = {a, b}; bf16v2_t r = __builtin_convertvector(v, bf16v2_t); return __builtin_bit_cast(unsigned, r); }
; DI f32x16 mfma32(bf16x8 a, bf16x8 b, f32x16 c) { return __builtin_amdgcn_mfma_f32_32x32x16_bf16(a, b, c, 0, 0, 0); }
; DI s16x4 trread(LAS unsigned char* p) { return __builtin_amdgcn_ds_read_tr16_b64_v4i16((LAS s16x4*)p); }
; DI bf16x8 cat4(s16x4 lo, s16x4 hi) { return __builtin_shufflevector(lo, hi, 0, 1, 2, 3, 4, 5, 6, 7); }
; template <int DQK, int KA8, int DV, bool BIAS, bool JOINT>
; DI void attn_core(LAS unsigned char* lds, const bf16_t* Qrow, const bf16_t* KpA, int ldkA, const bf16_t* KpB, int ldkB, const bf16_t* Vp, int ldv,
;                   int qb, int wid, int lane, const float* qng  , f32x16 (&O)[DV / 32]) {
;     ...
;             const bool far = (kt * 64 + 63 - q0w <= -91);
;             f32x16 S0, S1;
; #pragma unroll
;             for (int i = 0; i < 16; ++i) { S0[i] = 0.f; S1[i] = 0.f; }
; #pragma unroll
;             for (int s = 0; s < DQK / 16; ++s) {
;                 const bf16x8 k0 = *(LAS const bf16x8*)(kb + koff + 32 * s), k1 = *(LAS const bf16x8*)(kb + koff + 32 * KROW + 32 * s);
;                 S0 = mfma32(k0, qf[s], S0); S1 = mfma32(k1, qf[s], S1);
;             }
;     ...
; #pragma unroll
;             for (int half = 0; half < 2; ++half)
; #pragma unroll
;                 for (int s = 0; s < 2; ++s) {
;                     const f32x16& S = half ? S1 : S0;
;                     u32x4 pw; pw.x = pk2(S[8 * s], S[8 * s + 1]); pw.y = pk2(S[8 * s + 2], S[8 * s + 3]); pw.z = pk2(S[8 * s + 4], S[8 * s + 5]); pw.w = pk2(S[8 * s + 6], S[8 * s + 7]);
;                     const bf16x8 pf = __builtin_bit_cast(bf16x8, pw);
;                     LAS unsigned char* vr = vb + vtr + (32 * half + 16 * s) * VROW;
; #pragma unroll
;                     for (int dt = 0; dt < DV / 32; ++dt) {
;                         const bf16x8 vf = cat4(trread(vr + 64 * dt), trread(vr + 8 * VROW + 64 * dt));
;                         O[dt] = mfma32(vf, pf, O[dt]);
;                     }
.Laa_hv_6:
	ds_write_b128 v175, v[132:135] offset:18432
	ds_write_b128 v175, v[136:139] offset:28672
	ds_read_b64_tr_b16 v[168:169], v173 offset:44224
	ds_read_b64_tr_b16 v[170:171], v173 offset:46784
	s_waitcnt lgkmcnt(12)
	v_mfma_f32_32x32x16_bf16 v[32:47], v[148:151], v[96:99], v[32:47]
	ds_read_b64_tr_b16 v[140:141], v173 offset:49152
	ds_read_b64_tr_b16 v[142:143], v173 offset:51712
	s_waitcnt lgkmcnt(12)
	v_mfma_f32_32x32x16_bf16 v[48:63], v[152:155], v[96:99], v[48:63]
	ds_read_b64_tr_b16 v[144:145], v173 offset:49216
	ds_read_b64_tr_b16 v[146:147], v173 offset:51776
	s_waitcnt lgkmcnt(12)
	v_mfma_f32_32x32x16_bf16 v[0:15], v[156:159], v[100:103], v[0:15]
	ds_read_b64_tr_b16 v[148:149], v173 offset:49280
	ds_read_b64_tr_b16 v[150:151], v173 offset:51840
	s_waitcnt lgkmcnt(12)
	v_mfma_f32_32x32x16_bf16 v[16:31], v[160:163], v[100:103], v[16:31]
	ds_read_b64_tr_b16 v[152:153], v173 offset:49344
	ds_read_b64_tr_b16 v[154:155], v173 offset:51904
	s_waitcnt lgkmcnt(12)
	v_mfma_f32_32x32x16_bf16 v[32:47], v[164:167], v[100:103], v[32:47]
	ds_read_b64_tr_b16 v[156:157], v173 offset:54272
	ds_read_b64_tr_b16 v[158:159], v173 offset:56832
	s_waitcnt lgkmcnt(10)
	v_mfma_f32_32x32x16_bf16 v[48:63], v[168:171], v[100:103], v[48:63]
	ds_read_b64_tr_b16 v[160:161], v173 offset:54336
	ds_read_b64_tr_b16 v[162:163], v173 offset:56896
	s_waitcnt lgkmcnt(10)
	v_mfma_f32_32x32x16_bf16 v[0:15], v[140:143], v[104:107], v[0:15]
	ds_read_b64_tr_b16 v[164:165], v173 offset:54400
	ds_read_b64_tr_b16 v[166:167], v173 offset:56960
	s_waitcnt lgkmcnt(10)
	v_mfma_f32_32x32x16_bf16 v[16:31], v[144:147], v[104:107], v[16:31]
	ds_read_b64_tr_b16 v[168:169], v173 offset:54464
	ds_read_b64_tr_b16 v[170:171], v173 offset:57024
	s_waitcnt lgkmcnt(10)
	v_mfma_f32_32x32x16_bf16 v[32:47], v[148:151], v[104:107], v[32:47]
	s_waitcnt lgkmcnt(8)
	v_mfma_f32_32x32x16_bf16 v[48:63], v[152:155], v[104:107], v[48:63]
	s_waitcnt lgkmcnt(6)
	v_mfma_f32_32x32x16_bf16 v[0:15], v[156:159], v[108:111], v[0:15]
	s_waitcnt lgkmcnt(4)
	v_mfma_f32_32x32x16_bf16 v[16:31], v[160:163], v[108:111], v[16:31]
	s_waitcnt lgkmcnt(2)
	v_mfma_f32_32x32x16_bf16 v[32:47], v[164:167], v[108:111], v[32:47]
	s_waitcnt lgkmcnt(0)
	v_mfma_f32_32x32x16_bf16 v[48:63], v[168:171], v[108:111], v[48:63]
	s_branch .Laa_x0_end
.Laa_x0_qk:
	ds_read_b128 v[140:143], v172 offset:0
	ds_read_b128 v[144:147], v172 offset:4608
	ds_read_b128 v[148:151], v172 offset:32
	ds_read_b128 v[152:155], v172 offset:4640
	ds_read_b128 v[156:159], v172 offset:64
	ds_read_b128 v[160:163], v172 offset:4672
	s_waitcnt lgkmcnt(5)
	v_mfma_f32_32x32x16_bf16 v[64:79], v[140:143], v[112:115], 0
	ds_read_b128 v[164:167], v172 offset:96
	s_waitcnt lgkmcnt(5)
	v_mfma_f32_32x32x16_bf16 v[80:95], v[144:147], v[112:115], 0
	s_add_i32 s58, s24, 2
	s_cmp_lt_u32 s58, s17
	s_cbranch_scc1 .Laa_h3_7
	s_waitcnt vmcnt(2)
	s_branch .Laa_hk_8

; #define LAS __attribute__((address_space(3)))
; DI f32x16 mfma32(bf16x8 a, bf16x8 b, f32x16 c) { return __builtin_amdgcn_mfma_f32_32x32x16_bf16(a, b, c, 0, 0, 0); }
; template <int DQK, int KA8, int DV, bool BIAS, bool JOINT>
; DI void attn_core(LAS unsigned char* lds, const bf16_t* Qrow, const bf16_t* KpA, int ldkA, const bf16_t* KpB, int ldkB, const bf16_t* Vp, int ldv,
;                   int qb, int wid, int lane, const float* qng  , f32x16 (&O)[DV / 32]) {
;     ...
;     auto lstore = [&](int buf) {
; #pragma unroll
;         for (int i = 0; i < NL; ++i) { const int c = tid + i * 512;
;             if (i * 512 < NKC) { const int row = c / KC, cc = c % KC; *(LAS u32x4*)(lds + buf * STG + row * KROW + cc * 16) = stg[i]; }
;             else { const int c2 = c - NKC, row = c2 / VC, cc = c2 % VC; *(LAS u32x4*)(lds + buf * STG + 64 * KROW + row * VROW + cc * 16) = stg[i]; } }
;     };
;     ...
; #pragma unroll
;             for (int s = 0; s < DQK / 16; ++s) {
;                 const bf16x8 k0 = *(LAS const bf16x8*)(kb + koff + 32 * s), k1 = *(LAS const bf16x8*)(kb + koff + 32 * KROW + 32 * s);
;                 S0 = mfma32(k0, qf[s], S0); S1 = mfma32(k1, qf[s], S1);
;             }
.Laa_hv_9:
	ds_write_b128 v175, v[132:135] offset:18432
	ds_write_b128 v175, v[136:139] offset:28672
	ds_read_b128 v[168:171], v172 offset:4704
	s_waitcnt lgkmcnt(7)
	v_mfma_f32_32x32x16_bf16 v[64:79], v[148:151], v[116:119], v[64:79]
	s_waitcnt lgkmcnt(6)
	v_mfma_f32_32x32x16_bf16 v[80:95], v[152:155], v[116:119], v[80:95]
	s_waitcnt lgkmcnt(5)
	v_mfma_f32_32x32x16_bf16 v[64:79], v[156:159], v[120:123], v[64:79]
	s_waitcnt lgkmcnt(4)
	v_mfma_f32_32x32x16_bf16 v[80:95], v[160:163], v[120:123], v[80:95]
	s_waitcnt lgkmcnt(3)
	v_mfma_f32_32x32x16_bf16 v[64:79], v[164:167], v[124:127], v[64:79]
	s_waitcnt lgkmcnt(0)
	v_mfma_f32_32x32x16_bf16 v[80:95], v[168:171], v[124:127], v[80:95]
	s_branch .Laa_x0_end
.Laa_x0_none:
	s_add_i32 s58, s24, 2
	s_cmp_lt_u32 s58, s17
	s_cbranch_scc1 .Laa_h3_10
	s_waitcnt vmcnt(2)
	s_branch .Laa_hk_11

; #define LAS __attribute__((address_space(3)))
; DI int crow(int i, int hh) { return (i & 3) + 8 * (i >> 2) + 4 * hh; }
; DI f32x16 mfma32(bf16x8 a, bf16x8 b, f32x16 c) { return __builtin_amdgcn_mfma_f32_32x32x16_bf16(a, b, c, 0, 0, 0); }
; template <int DQK, int KA8, int DV, bool BIAS, bool JOINT>
; DI void attn_core(LAS unsigned char* lds, const bf16_t* Qrow, const bf16_t* KpA, int ldkA, const bf16_t* KpB, int ldkB, const bf16_t* Vp, int ldv,
;                   int qb, int wid, int lane, const float* qng  , f32x16 (&O)[DV / 32]) {
;     ...
;         if (kt + 1 < nkt) gload(kt + 1);
;         if (JOINT && kt <= myc) {
;             LAS unsigned char* kb = lds + (kt & 1) * STG; LAS unsigned char* vb = kb + 64 * KROW;
;             const bool far = (kt * 64 + 63 - q0w <= -91);
;             f32x16 S0, S1;
; #pragma unroll
;             for (int i = 0; i < 16; ++i) { S0[i] = 0.f; S1[i] = 0.f; }
; #pragma unroll
;             for (int s = 0; s < DQK / 16; ++s) {
;                 const bf16x8 k0 = *(LAS const bf16x8*)(kb + koff + 32 * s), k1 = *(LAS const bf16x8*)(kb + koff + 32 * KROW + 32 * s);
;                 S0 = mfma32(k0, qf[s], S0); S1 = mfma32(k1, qf[s], S1);
;             }
;             if (BIAS && !far) {
;                 const int rb = kt * 64 - (q0w + l32) + 128;
; #pragma unroll
;                 for (int i = 0; i < 16; ++i) { const int i0 = rb + crow(i, hh); S0[i] += btab[i0 < 0 ? 0 : i0]; S1[i] += btab[i0 + 32 < 0 ? 0 : i0 + 32]; }
;             }
.Laa_hv_12:
	ds_write_b128 v175, v[132:135] offset:18432
	ds_write_b128 v175, v[136:139] offset:28672
.Laa_x0_end:
	s_waitcnt lgkmcnt(0)
	s_barrier
	s_add_i32 s58, s24, 2
	s_cmp_lt_u32 s58, s17
	s_cbranch_scc0 .Laa_y0_nold
	global_load_dwordx4 v[132:135], v177, s[34:35]
	global_load_dwordx4 v[136:139], v182, s[34:35]
	s_add_u32 s34, s34, 0x100000
	s_addc_u32 s35, s35, 0
	global_load_dwordx4 v[128:131], v176, s[30:31]
	s_add_u32 s30, s30, 0x100000
	s_addc_u32 s31, s31, 0
.Laa_y0_nold:
	s_cmp_gt_u32 s24, s25
	s_cbranch_scc1 .Laa_y0_end
	s_nop 15
	s_lshl_b32 s58, s24, 6
	s_add_i32 s60, s58, 154
	s_cmp_gt_i32 s60, s43
	s_cbranch_scc0 .Laa_y0_nobias
	v_add_u32_e32 v186, s58, v203
	v_max_i32_e32 v188, 0xffffffe0, v186
	v_max_i32_e32 v187, 0, v186
	v_lshlrev_b32_e32 v187, 2, v187
	v_lshlrev_b32_e32 v188, 2, v188
	ds_read_b32 v140, v187 offset:59392
	ds_read_b32 v156, v188 offset:59520
	v_add_u32_e32 v189, 1, v186
	v_max_i32_e32 v190, 0xffffffe0, v189
	v_max_i32_e32 v189, 0, v189
	v_lshlrev_b32_e32 v189, 2, v189
	v_lshlrev_b32_e32 v190, 2, v190
	ds_read_b32 v141, v189 offset:59392
	ds_read_b32 v157, v190 offset:59520
	v_add_u32_e32 v193, 2, v186
	v_max_i32_e32 v195, 0xffffffe0, v193
	v_max_i32_e32 v193, 0, v193
	v_lshlrev_b32_e32 v193, 2, v193
	v_lshlrev_b32_e32 v195, 2, v195
	ds_read_b32 v142, v193 offset:59392
	ds_read_b32 v158, v195 offset:59520
	v_add_u32_e32 v196, 3, v186
	v_max_i32_e32 v236, 0xffffffe0, v196
	v_max_i32_e32 v196, 0, v196
	v_lshlrev_b32_e32 v196, 2, v196
	v_lshlrev_b32_e32 v236, 2, v236
	ds_read_b32 v143, v196 offset:59392
	ds_read_b32 v159, v236 offset:59520
	s_waitcnt lgkmcnt(0)
	v_add_f32_e32 v64, v64, v140
	v_add_f32_e32 v80, v80, v156
	v_add_f32_e32 v65, v65, v141
	v_add_f32_e32 v81, v81, v157
	v_add_f32_e32 v66, v66, v142
	v_add_f32_e32 v82, v82, v158
	v_add_f32_e32 v67, v67, v143
	v_add_f32_e32 v83, v83, v159
	v_add_u32_e32 v187, 8, v186
	v_max_i32_e32 v188, 0xffffffe0, v187
	v_max_i32_e32 v187, 0, v187
	v_lshlrev_b32_e32 v187, 2, v187
	v_lshlrev_b32_e32 v188, 2, v188
	ds_read_b32 v144, v187 offset:59392
	ds_read_b32 v160, v188 offset:59520
	v_add_u32_e32 v189, 9, v186
	v_max_i32_e32 v190, 0xffffffe0, v189
	v_max_i32_e32 v189, 0, v189
	v_lshlrev_b32_e32 v189, 2, v189
	v_lshlrev_b32_e32 v190, 2, v190
	ds_read_b32 v145, v189 offset:59392
	ds_read_b32 v161, v190 offset:59520
	v_add_u32_e32 v193, 10, v186
	v_max_i32_e32 v195, 0xffffffe0, v193
	v_max_i32_e32 v193, 0, v193
	v_lshlrev_b32_e32 v193, 2, v193
	v_lshlrev_b32_e32 v195, 2, v195
	ds_read_b32 v146, v193 offset:59392
	ds_read_b32 v162, v195 offset:59520
	v_add_u32_e32 v196, 11, v186
	v_max_i32_e32 v236, 0xffffffe0, v196
	v_max_i32_e32 v196, 0, v196
	v_lshlrev_b32_e32 v196, 2, v196
	v_lshlrev_b32_e32 v236, 2, v236
	ds_read_b32 v147, v196 offset:59392
	ds_read_b32 v163, v236 offset:59520
	s_waitcnt lgkmcnt(0)
	v_add_f32_e32 v68, v68, v144
	v_add_f32_e32 v84, v84, v160
	v_add_f32_e32 v69, v69, v145
	v_add_f32_e32 v85, v85, v161
	v_add_f32_e32 v70, v70, v146
	v_add_f32_e32 v86, v86, v162
	v_add_f32_e32 v71, v71, v147
	v_add_f32_e32 v87, v87, v163
	v_add_u32_e32 v187, 16, v186
	v_max_i32_e32 v188, 0xffffffe0, v187
	v_max_i32_e32 v187, 0, v187
	v_lshlrev_b32_e32 v187, 2, v187
	v_lshlrev_b32_e32 v188, 2, v188
	ds_read_b32 v148, v187 offset:59392
	ds_read_b32 v164, v188 offset:59520
	v_add_u32_e32 v189, 17, v186
	v_max_i32_e32 v190, 0xffffffe0, v189
	v_max_i32_e32 v189, 0, v189
	v_lshlrev_b32_e32 v189, 2, v189
	v_lshlrev_b32_e32 v190, 2, v190
	ds_read_b32 v149, v189 offset:59392
	ds_read_b32 v165, v190 offset:59520
	v_add_u32_e32 v193, 18, v186
	v_max_i32_e32 v195, 0xffffffe0, v193
	v_max_i32_e32 v193, 0, v193
	v_lshlrev_b32_e32 v193, 2, v193
	v_lshlrev_b32_e32 v195, 2, v195
	ds_read_b32 v150, v193 offset:59392
	ds_read_b32 v166, v195 offset:59520
	v_add_u32_e32 v196, 19, v186
	v_max_i32_e32 v236, 0xffffffe0, v196
	v_max_i32_e32 v196, 0, v196
	v_lshlrev_b32_e32 v196, 2, v196
	v_lshlrev_b32_e32 v236, 2, v236
	ds_read_b32 v151, v196 offset:59392
	ds_read_b32 v167, v236 offset:59520
	s_waitcnt lgkmcnt(0)
	v_add_f32_e32 v72, v72, v148
	v_add_f32_e32 v88, v88, v164
	v_add_f32_e32 v73, v73, v149
	v_add_f32_e32 v89, v89, v165
	v_add_f32_e32 v74, v74, v150
	v_add_f32_e32 v90, v90, v166
	v_add_f32_e32 v75, v75, v151
	v_add_f32_e32 v91, v91, v167
	v_add_u32_e32 v187, 24, v186
	v_max_i32_e32 v188, 0xffffffe0, v187
	v_max_i32_e32 v187, 0, v187
	v_lshlrev_b32_e32 v187, 2, v187
	v_lshlrev_b32_e32 v188, 2, v188
	ds_read_b32 v152, v187 offset:59392
	ds_read_b32 v168, v188 offset:59520
	v_add_u32_e32 v189, 25, v186
	v_max_i32_e32 v190, 0xffffffe0, v189
	v_max_i32_e32 v189, 0, v189
	v_lshlrev_b32_e32 v189, 2, v189
	v_lshlrev_b32_e32 v190, 2, v190
	ds_read_b32 v153, v189 offset:59392
	ds_read_b32 v169, v190 offset:59520
	v_add_u32_e32 v193, 26, v186
	v_max_i32_e32 v195, 0xffffffe0, v193
	v_max_i32_e32 v193, 0, v193
	v_lshlrev_b32_e32 v193, 2, v193
	v_lshlrev_b32_e32 v195, 2, v195
	ds_read_b32 v154, v193 offset:59392
	ds_read_b32 v170, v195 offset:59520
	v_add_u32_e32 v196, 27, v186
	v_max_i32_e32 v236, 0xffffffe0, v196
	v_max_i32_e32 v196, 0, v196
	v_lshlrev_b32_e32 v196, 2, v196
	v_lshlrev_b32_e32 v236, 2, v236
	ds_read_b32 v155, v196 offset:59392
	ds_read_b32 v171, v236 offset:59520
	s_waitcnt lgkmcnt(0)
	v_add_f32_e32 v76, v76, v152
	v_add_f32_e32 v92, v92, v168
	v_add_f32_e32 v77, v77, v153
	v_add_f32_e32 v93, v93, v169
	v_add_f32_e32 v78, v78, v154
	v_add_f32_e32 v94, v94, v170
	v_add_f32_e32 v79, v79, v155
	v_add_f32_e32 v95, v95, v171

; #define LAS __attribute__((address_space(3)))
; DI unsigned pk2(float a, float b) { f32x2 v = {a, b}; bf16v2_t r = __builtin_convertvector(v, bf16v2_t); return __builtin_bit_cast(unsigned, r); }
; DI f32x16 mfma32(bf16x8 a, bf16x8 b, f32x16 c) { return __builtin_amdgcn_mfma_f32_32x32x16_bf16(a, b, c, 0, 0, 0); }
; DI s16x4 trread(LAS unsigned char* p) { return __builtin_amdgcn_ds_read_tr16_b64_v4i16((LAS s16x4*)p); }
; DI bf16x8 cat4(s16x4 lo, s16x4 hi) { return __builtin_shufflevector(lo, hi, 0, 1, 2, 3, 4, 5, 6, 7); }
; template <int DQK, int KA8, int DV, bool BIAS, bool JOINT>
; DI void attn_core(LAS unsigned char* lds, const bf16_t* Qrow, const bf16_t* KpA, int ldkA, const bf16_t* KpB, int ldkB, const bf16_t* Vp, int ldv,
;                   int qb, int wid, int lane, const float* qng  , f32x16 (&O)[DV / 32]) {
;     ...
;             for (int half = 0; half < 2; ++half)
; #pragma unroll
;                 for (int s = 0; s < 2; ++s) {
;                     const f32x16& S = half ? S1 : S0;
;                     u32x4 pw; pw.x = pk2(S[8 * s], S[8 * s + 1]); pw.y = pk2(S[8 * s + 2], S[8 * s + 3]); pw.z = pk2(S[8 * s + 4], S[8 * s + 5]); pw.w = pk2(S[8 * s + 6], S[8 * s + 7]);
;                     const bf16x8 pf = __builtin_bit_cast(bf16x8, pw);
;                     LAS unsigned char* vr = vb + vtr + (32 * half + 16 * s) * VROW;
; #pragma unroll
;                     for (int dt = 0; dt < DV / 32; ++dt) {
;                         const bf16x8 vf = cat4(trread(vr + 64 * dt), trread(vr + 8 * VROW + 64 * dt));
;                         O[dt] = mfma32(vf, pf, O[dt]);
;                     }
;                 }
.Laa_y0_end:
	s_barrier
	s_add_i32 s59, s24, 1
	s_add_i32 s58, s25, 1
	s_cmp_gt_u32 s59, s58
	s_cbranch_scc1 .Laa_x1_none
	s_cmp_eq_u32 s59, s58
	s_cbranch_scc1 .Laa_x1_pv
	ds_read_b64_tr_b16 v[140:141], v173 offset:18432
	ds_read_b64_tr_b16 v[142:143], v173 offset:20992
	ds_read_b64_tr_b16 v[144:145], v173 offset:18496
	ds_read_b64_tr_b16 v[146:147], v173 offset:21056
	ds_read_b64_tr_b16 v[148:149], v173 offset:18560
	ds_read_b64_tr_b16 v[150:151], v173 offset:21120
	ds_read_b64_tr_b16 v[152:153], v173 offset:18624
	ds_read_b64_tr_b16 v[154:155], v173 offset:21184
	ds_read_b64_tr_b16 v[156:157], v173 offset:23552
	ds_read_b64_tr_b16 v[158:159], v173 offset:26112
	ds_read_b64_tr_b16 v[160:161], v173 offset:23616
	ds_read_b64_tr_b16 v[162:163], v173 offset:26176
	s_waitcnt lgkmcnt(10)
	v_mfma_f32_32x32x16_bf16 v[0:15], v[140:143], v[96:99], v[0:15]
	ds_read_b64_tr_b16 v[164:165], v173 offset:23680
	ds_read_b64_tr_b16 v[166:167], v173 offset:26240
	s_waitcnt lgkmcnt(10)
	v_mfma_f32_32x32x16_bf16 v[16:31], v[144:147], v[96:99], v[16:31]
	s_add_i32 s58, s59, 2
	s_cmp_lt_u32 s58, s17
	s_cbranch_scc1 .Laa_h3_13
	s_waitcnt vmcnt(0)
	s_branch .Laa_hv_15

; #define LAS __attribute__((address_space(3)))
; DI int crow(int i, int hh) { return (i & 3) + 8 * (i >> 2) + 4 * hh; }
; template <int DQK, int KA8, int DV, bool BIAS, bool JOINT>
; DI void attn_core(LAS unsigned char* lds, const bf16_t* Qrow, const bf16_t* KpA, int ldkA, const bf16_t* KpB, int ldkB, const bf16_t* Vp, int ldv,
;                   int qb, int wid, int lane, const float* qng  , f32x16 (&O)[DV / 32]) {
;     ...
;             const bool far = (kt * 64 + 63 - q0w <= -91);
;             f32x16 S0, S1;
; #pragma unroll
;             for (int i = 0; i < 16; ++i) { S0[i] = 0.f; S1[i] = 0.f; }
; #pragma unroll
;             for (int s = 0; s < DQK / 16; ++s) {
;                 const bf16x8 k0 = *(LAS const bf16x8*)(kb + koff + 32 * s), k1 = *(LAS const bf16x8*)(kb + koff + 32 * KROW + 32 * s);
;                 S0 = mfma32(k0, qf[s], S0); S1 = mfma32(k1, qf[s], S1);
;             }
;             if (BIAS && !far) {
;                 const int rb = kt * 64 - (q0w + l32) + 128;
; #pragma unroll
;                 for (int i = 0; i < 16; ++i) { const int i0 = rb + crow(i, hh); S0[i] += btab[i0 < 0 ? 0 : i0]; S1[i] += btab[i0 + 32 < 0 ? 0 : i0 + 32]; }
;             }
;             if (mnz) {
; #pragma unroll
;                 for (int i = 0; i < 16; ++i) { S0[i] -= m; S1[i] -= m; }
;             }
;             float mx = fmaxf(S0[0], S1[0]);
; #pragma unroll
;             for (int i = 1; i < 16; ++i) mx = fmaxf(mx, fmaxf(S0[i], S1[i]));
;             mx = fmaxf(mx, __shfl_xor(mx, 32));
;             if (__any(mx > 64.f || (kt == 0 && mx < -64.f))) {
;                 const float dm = (mx > 64.f || (kt == 0 && mx < -64.f)) ? mx : 0.f, alpha = __builtin_amdgcn_exp2f(-dm); m += dm; mnz = true;
;                 l *= alpha;
; #pragma unroll
;                 for (int dt = 0; dt < DV / 32; ++dt) O[dt] *= alpha;
; #pragma unroll
;                 for (int i = 0; i < 16; ++i) { S0[i] -= dm; S1[i] -= dm; }
;             }
;             float ps = 0.f;
; #pragma unroll
;             for (int i = 0; i < 16; ++i) { S0[i] = __builtin_amdgcn_exp2f(S0[i]); S1[i] = __builtin_amdgcn_exp2f(S1[i]); ps += S0[i] + S1[i]; }
;             l += ps;
; #pragma unroll
;             for (int half = 0; half < 2; ++half)
; #pragma unroll
;                 for (int s = 0; s < 2; ++s) {
;                     const f32x16& S = half ? S1 : S0;
.Laa_hk_14:
	ds_write_b128 v174, v[204:207] offset:0
.Laa_hv_15:
	ds_write_b128 v175, v[208:211] offset:38912
	ds_write_b128 v175, v[212:215] offset:49152
	ds_read_b64_tr_b16 v[168:169], v173 offset:23744
	ds_read_b64_tr_b16 v[170:171], v173 offset:26304
	s_waitcnt lgkmcnt(12)
	v_mfma_f32_32x32x16_bf16 v[32:47], v[148:151], v[96:99], v[32:47]
	ds_read_b64_tr_b16 v[140:141], v173 offset:28672
	ds_read_b64_tr_b16 v[142:143], v173 offset:31232
	s_waitcnt lgkmcnt(12)
	v_mfma_f32_32x32x16_bf16 v[48:63], v[152:155], v[96:99], v[48:63]
	ds_read_b64_tr_b16 v[144:145], v173 offset:28736
	ds_read_b64_tr_b16 v[146:147], v173 offset:31296
	s_waitcnt lgkmcnt(12)
	v_mfma_f32_32x32x16_bf16 v[0:15], v[156:159], v[100:103], v[0:15]
	ds_read_b64_tr_b16 v[148:149], v173 offset:28800
	ds_read_b64_tr_b16 v[150:151], v173 offset:31360
	s_waitcnt lgkmcnt(12)
	v_mfma_f32_32x32x16_bf16 v[16:31], v[160:163], v[100:103], v[16:31]
	ds_read_b64_tr_b16 v[152:153], v173 offset:28864
	ds_read_b64_tr_b16 v[154:155], v173 offset:31424
	s_waitcnt lgkmcnt(12)
	v_mfma_f32_32x32x16_bf16 v[32:47], v[164:167], v[100:103], v[32:47]
	ds_read_b64_tr_b16 v[156:157], v173 offset:33792
	ds_read_b64_tr_b16 v[158:159], v173 offset:36352
	s_waitcnt lgkmcnt(10)
	v_mfma_f32_32x32x16_bf16 v[48:63], v[168:171], v[100:103], v[48:63]
	ds_read_b64_tr_b16 v[160:161], v173 offset:33856
	ds_read_b64_tr_b16 v[162:163], v173 offset:36416
	s_waitcnt lgkmcnt(10)
	v_mfma_f32_32x32x16_bf16 v[0:15], v[140:143], v[104:107], v[0:15]
	ds_read_b64_tr_b16 v[164:165], v173 offset:33920
	ds_read_b64_tr_b16 v[166:167], v173 offset:36480
	s_waitcnt lgkmcnt(10)
	v_mfma_f32_32x32x16_bf16 v[16:31], v[144:147], v[104:107], v[16:31]
	ds_read_b64_tr_b16 v[168:169], v173 offset:33984
	ds_read_b64_tr_b16 v[170:171], v173 offset:36544
	s_waitcnt lgkmcnt(10)
	v_mfma_f32_32x32x16_bf16 v[32:47], v[148:151], v[104:107], v[32:47]
	ds_read_b128 v[140:143], v172 offset:9216
	s_waitcnt lgkmcnt(9)
	v_mfma_f32_32x32x16_bf16 v[48:63], v[152:155], v[104:107], v[48:63]
	ds_read_b128 v[144:147], v172 offset:13824
	s_waitcnt lgkmcnt(8)
	v_mfma_f32_32x32x16_bf16 v[0:15], v[156:159], v[108:111], v[0:15]
	ds_read_b128 v[148:151], v172 offset:9248
	s_waitcnt lgkmcnt(7)
	v_mfma_f32_32x32x16_bf16 v[16:31], v[160:163], v[108:111], v[16:31]
	ds_read_b128 v[152:155], v172 offset:13856
	s_waitcnt lgkmcnt(6)
	v_mfma_f32_32x32x16_bf16 v[32:47], v[164:167], v[108:111], v[32:47]
	ds_read_b128 v[156:159], v172 offset:9280
	s_waitcnt lgkmcnt(5)
	v_mfma_f32_32x32x16_bf16 v[48:63], v[168:171], v[108:111], v[48:63]
	ds_read_b128 v[160:163], v172 offset:13888
	s_waitcnt lgkmcnt(5)
	v_mfma_f32_32x32x16_bf16 v[64:79], v[140:143], v[112:115], 0
	ds_read_b128 v[164:167], v172 offset:9312
	s_waitcnt lgkmcnt(5)
	v_mfma_f32_32x32x16_bf16 v[80:95], v[144:147], v[112:115], 0
	ds_read_b128 v[168:171], v172 offset:13920
	s_waitcnt lgkmcnt(5)
	v_mfma_f32_32x32x16_bf16 v[64:79], v[148:151], v[116:119], v[64:79]
	s_waitcnt lgkmcnt(4)
	v_mfma_f32_32x32x16_bf16 v[80:95], v[152:155], v[116:119], v[80:95]
	s_waitcnt lgkmcnt(3)
	v_mfma_f32_32x32x16_bf16 v[64:79], v[156:159], v[120:123], v[64:79]
	s_waitcnt lgkmcnt(2)
	v_mfma_f32_32x32x16_bf16 v[80:95], v[160:163], v[120:123], v[80:95]
	s_waitcnt lgkmcnt(1)
	v_mfma_f32_32x32x16_bf16 v[64:79], v[164:167], v[124:127], v[64:79]
	s_waitcnt lgkmcnt(0)
	v_mfma_f32_32x32x16_bf16 v[80:95], v[168:171], v[124:127], v[80:95]
	s_branch .Laa_x1_end
.Laa_x1_pv:
	ds_read_b64_tr_b16 v[140:141], v173 offset:18432
	ds_read_b64_tr_b16 v[142:143], v173 offset:20992
	ds_read_b64_tr_b16 v[144:145], v173 offset:18496
	ds_read_b64_tr_b16 v[146:147], v173 offset:21056
	ds_read_b64_tr_b16 v[148:149], v173 offset:18560
	ds_read_b64_tr_b16 v[150:151], v173 offset:21120
	ds_read_b64_tr_b16 v[152:153], v173 offset:18624
	ds_read_b64_tr_b16 v[154:155], v173 offset:21184
	ds_read_b64_tr_b16 v[156:157], v173 offset:23552
	ds_read_b64_tr_b16 v[158:159], v173 offset:26112
	ds_read_b64_tr_b16 v[160:161], v173 offset:23616
	ds_read_b64_tr_b16 v[162:163], v173 offset:26176
	s_waitcnt lgkmcnt(10)
	v_mfma_f32_32x32x16_bf16 v[0:15], v[140:143], v[96:99], v[0:15]
	ds_read_b64_tr_b16 v[164:165], v173 offset:23680
	ds_read_b64_tr_b16 v[166:167], v173 offset:26240
	s_waitcnt lgkmcnt(10)
	v_mfma_f32_32x32x16_bf16 v[16:31], v[144:147], v[96:99], v[16:31]
	s_add_i32 s58, s59, 2
	s_cmp_lt_u32 s58, s17
	s_cbranch_scc1 .Laa_h3_16
	s_waitcnt vmcnt(0)
	s_branch .Laa_hv_18

; #define LAS __attribute__((address_space(3)))
; DI unsigned pk2(float a, float b) { f32x2 v = {a, b}; bf16v2_t r = __builtin_convertvector(v, bf16v2_t); return __builtin_bit_cast(unsigned, r); }
; DI f32x16 mfma32(bf16x8 a, bf16x8 b, f32x16 c) { return __builtin_amdgcn_mfma_f32_32x32x16_bf16(a, b, c, 0, 0, 0); }
; DI s16x4 trread(LAS unsigned char* p) { return __builtin_amdgcn_ds_read_tr16_b64_v4i16((LAS s16x4*)p); }
; DI bf16x8 cat4(s16x4 lo, s16x4 hi) { return __builtin_shufflevector(lo, hi, 0, 1, 2, 3, 4, 5, 6, 7); }
; template <int DQK, int KA8, int DV, bool BIAS, bool JOINT>
; DI void attn_core(LAS unsigned char* lds, const bf16_t* Qrow, const bf16_t* KpA, int ldkA, const bf16_t* KpB, int ldkB, const bf16_t* Vp, int ldv,
;                   int qb, int wid, int lane, const float* qng  , f32x16 (&O)[DV / 32]) {
;     ...
;             for (int half = 0; half < 2; ++half)
; #pragma unroll
;                 for (int s = 0; s < 2; ++s) {
;                     const f32x16& S = half ? S1 : S0;
;                     u32x4 pw; pw.x = pk2(S[8 * s], S[8 * s + 1]); pw.y = pk2(S[8 * s + 2], S[8 * s + 3]); pw.z = pk2(S[8 * s + 4], S[8 * s + 5]); pw.w = pk2(S[8 * s + 6], S[8 * s + 7]);
;                     const bf16x8 pf = __builtin_bit_cast(bf16x8, pw);
;                     LAS unsigned char* vr = vb + vtr + (32 * half + 16 * s) * VROW;
; #pragma unroll
;                     for (int dt = 0; dt < DV / 32; ++dt) {
;                         const bf16x8 vf = cat4(trread(vr + 64 * dt), trread(vr + 8 * VROW + 64 * dt));
;                         O[dt] = mfma32(vf, pf, O[dt]);
;                     }
;                 }
.Laa_hv_18:
	ds_write_b128 v175, v[208:211] offset:38912
	ds_write_b128 v175, v[212:215] offset:49152
	ds_read_b64_tr_b16 v[168:169], v173 offset:23744
	ds_read_b64_tr_b16 v[170:171], v173 offset:26304
	s_waitcnt lgkmcnt(12)
	v_mfma_f32_32x32x16_bf16 v[32:47], v[148:151], v[96:99], v[32:47]
	ds_read_b64_tr_b16 v[140:141], v173 offset:28672
	ds_read_b64_tr_b16 v[142:143], v173 offset:31232
	s_waitcnt lgkmcnt(12)
	v_mfma_f32_32x32x16_bf16 v[48:63], v[152:155], v[96:99], v[48:63]
	ds_read_b64_tr_b16 v[144:145], v173 offset:28736
	ds_read_b64_tr_b16 v[146:147], v173 offset:31296
	s_waitcnt lgkmcnt(12)
	v_mfma_f32_32x32x16_bf16 v[0:15], v[156:159], v[100:103], v[0:15]
	ds_read_b64_tr_b16 v[148:149], v173 offset:28800
	ds_read_b64_tr_b16 v[150:151], v173 offset:31360
	s_waitcnt lgkmcnt(12)
	v_mfma_f32_32x32x16_bf16 v[16:31], v[160:163], v[100:103], v[16:31]
	ds_read_b64_tr_b16 v[152:153], v173 offset:28864
	ds_read_b64_tr_b16 v[154:155], v173 offset:31424
	s_waitcnt lgkmcnt(12)
	v_mfma_f32_32x32x16_bf16 v[32:47], v[164:167], v[100:103], v[32:47]
	ds_read_b64_tr_b16 v[156:157], v173 offset:33792
	ds_read_b64_tr_b16 v[158:159], v173 offset:36352
	s_waitcnt lgkmcnt(10)
	v_mfma_f32_32x32x16_bf16 v[48:63], v[168:171], v[100:103], v[48:63]
	ds_read_b64_tr_b16 v[160:161], v173 offset:33856
	ds_read_b64_tr_b16 v[162:163], v173 offset:36416
	s_waitcnt lgkmcnt(10)
	v_mfma_f32_32x32x16_bf16 v[0:15], v[140:143], v[104:107], v[0:15]
	ds_read_b64_tr_b16 v[164:165], v173 offset:33920
	ds_read_b64_tr_b16 v[166:167], v173 offset:36480
	s_waitcnt lgkmcnt(10)
	v_mfma_f32_32x32x16_bf16 v[16:31], v[144:147], v[104:107], v[16:31]
	ds_read_b64_tr_b16 v[168:169], v173 offset:33984
	ds_read_b64_tr_b16 v[170:171], v173 offset:36544
	s_waitcnt lgkmcnt(10)
	v_mfma_f32_32x32x16_bf16 v[32:47], v[148:151], v[104:107], v[32:47]
	s_waitcnt lgkmcnt(8)
	v_mfma_f32_32x32x16_bf16 v[48:63], v[152:155], v[104:107], v[48:63]
	s_waitcnt lgkmcnt(6)
	v_mfma_f32_32x32x16_bf16 v[0:15], v[156:159], v[108:111], v[0:15]
	s_waitcnt lgkmcnt(4)
	v_mfma_f32_32x32x16_bf16 v[16:31], v[160:163], v[108:111], v[16:31]
	s_waitcnt lgkmcnt(2)
	v_mfma_f32_32x32x16_bf16 v[32:47], v[164:167], v[108:111], v[32:47]
	s_waitcnt lgkmcnt(0)
	v_mfma_f32_32x32x16_bf16 v[48:63], v[168:171], v[108:111], v[48:63]
	s_branch .Laa_x1_end
.Laa_x1_none:
	s_add_i32 s58, s59, 2
	s_cmp_lt_u32 s58, s17
	s_cbranch_scc1 .Laa_h3_19
	s_waitcnt vmcnt(0)
	s_branch .Laa_hv_21

; #define LAS __attribute__((address_space(3)))
; DI int crow(int i, int hh) { return (i & 3) + 8 * (i >> 2) + 4 * hh; }
; DI f32x16 mfma32(bf16x8 a, bf16x8 b, f32x16 c) { return __builtin_amdgcn_mfma_f32_32x32x16_bf16(a, b, c, 0, 0, 0); }
; template <int DQK, int KA8, int DV, bool BIAS, bool JOINT>
; DI void attn_core(LAS unsigned char* lds, const bf16_t* Qrow, const bf16_t* KpA, int ldkA, const bf16_t* KpB, int ldkB, const bf16_t* Vp, int ldv,
;                   int qb, int wid, int lane, const float* qng  , f32x16 (&O)[DV / 32]) {
;     ...
;         if (kt + 1 < nkt) gload(kt + 1);
;         if (JOINT && kt <= myc) {
;             LAS unsigned char* kb = lds + (kt & 1) * STG; LAS unsigned char* vb = kb + 64 * KROW;
;             const bool far = (kt * 64 + 63 - q0w <= -91);
;             f32x16 S0, S1;
; #pragma unroll
;             for (int i = 0; i < 16; ++i) { S0[i] = 0.f; S1[i] = 0.f; }
; #pragma unroll
;             for (int s = 0; s < DQK / 16; ++s) {
;                 const bf16x8 k0 = *(LAS const bf16x8*)(kb + koff + 32 * s), k1 = *(LAS const bf16x8*)(kb + koff + 32 * KROW + 32 * s);
;                 S0 = mfma32(k0, qf[s], S0); S1 = mfma32(k1, qf[s], S1);
;             }
;             if (BIAS && !far) {
;                 const int rb = kt * 64 - (q0w + l32) + 128;
; #pragma unroll
;                 for (int i = 0; i < 16; ++i) { const int i0 = rb + crow(i, hh); S0[i] += btab[i0 < 0 ? 0 : i0]; S1[i] += btab[i0 + 32 < 0 ? 0 : i0 + 32]; }
;             }
.Laa_hv_21:
	ds_write_b128 v175, v[208:211] offset:38912
	ds_write_b128 v175, v[212:215] offset:49152
.Laa_x1_end:
	s_waitcnt lgkmcnt(0)
	s_barrier
	s_add_i32 s58, s59, 2
	s_cmp_lt_u32 s58, s17
	s_cbranch_scc0 .Laa_y1_nold
	global_load_dwordx4 v[208:211], v177, s[34:35]
	global_load_dwordx4 v[212:215], v182, s[34:35]
	s_add_u32 s34, s34, 0x100000
	s_addc_u32 s35, s35, 0
	s_add_i32 s58, s59, 3
	s_cmp_lt_u32 s58, s17
	s_cbranch_scc0 .Laa_y1_nold
	global_load_dwordx4 v[204:207], v176, s[30:31]
	s_add_u32 s30, s30, 0x100000
	s_addc_u32 s31, s31, 0
.Laa_y1_nold:
	s_cmp_gt_u32 s59, s25
	s_cbranch_scc1 .Laa_y1_end
	s_nop 15
	s_lshl_b32 s58, s59, 6
	s_add_i32 s60, s58, 154
	s_cmp_gt_i32 s60, s43
	s_cbranch_scc0 .Laa_y1_nobias
	v_add_u32_e32 v186, s58, v203
	v_max_i32_e32 v188, 0xffffffe0, v186
	v_max_i32_e32 v187, 0, v186
	v_lshlrev_b32_e32 v187, 2, v187
	v_lshlrev_b32_e32 v188, 2, v188
	ds_read_b32 v140, v187 offset:59392
	ds_read_b32 v156, v188 offset:59520
	v_add_u32_e32 v189, 1, v186
	v_max_i32_e32 v190, 0xffffffe0, v189
	v_max_i32_e32 v189, 0, v189
	v_lshlrev_b32_e32 v189, 2, v189
	v_lshlrev_b32_e32 v190, 2, v190
	ds_read_b32 v141, v189 offset:59392
	ds_read_b32 v157, v190 offset:59520
	v_add_u32_e32 v193, 2, v186
	v_max_i32_e32 v195, 0xffffffe0, v193
	v_max_i32_e32 v193, 0, v193
	v_lshlrev_b32_e32 v193, 2, v193
	v_lshlrev_b32_e32 v195, 2, v195
	ds_read_b32 v142, v193 offset:59392
	ds_read_b32 v158, v195 offset:59520
	v_add_u32_e32 v196, 3, v186
	v_max_i32_e32 v236, 0xffffffe0, v196
	v_max_i32_e32 v196, 0, v196
	v_lshlrev_b32_e32 v196, 2, v196
	v_lshlrev_b32_e32 v236, 2, v236
	ds_read_b32 v143, v196 offset:59392
	ds_read_b32 v159, v236 offset:59520
	s_waitcnt lgkmcnt(0)
	v_add_f32_e32 v64, v64, v140
	v_add_f32_e32 v80, v80, v156
	v_add_f32_e32 v65, v65, v141
	v_add_f32_e32 v81, v81, v157
	v_add_f32_e32 v66, v66, v142
	v_add_f32_e32 v82, v82, v158
	v_add_f32_e32 v67, v67, v143
	v_add_f32_e32 v83, v83, v159
	v_add_u32_e32 v187, 8, v186
	v_max_i32_e32 v188, 0xffffffe0, v187
	v_max_i32_e32 v187, 0, v187
	v_lshlrev_b32_e32 v187, 2, v187
	v_lshlrev_b32_e32 v188, 2, v188
	ds_read_b32 v144, v187 offset:59392
	ds_read_b32 v160, v188 offset:59520
	v_add_u32_e32 v189, 9, v186
	v_max_i32_e32 v190, 0xffffffe0, v189
	v_max_i32_e32 v189, 0, v189
	v_lshlrev_b32_e32 v189, 2, v189
	v_lshlrev_b32_e32 v190, 2, v190
	ds_read_b32 v145, v189 offset:59392
	ds_read_b32 v161, v190 offset:59520
	v_add_u32_e32 v193, 10, v186
	v_max_i32_e32 v195, 0xffffffe0, v193
	v_max_i32_e32 v193, 0, v193
	v_lshlrev_b32_e32 v193, 2, v193
	v_lshlrev_b32_e32 v195, 2, v195
	ds_read_b32 v146, v193 offset:59392
	ds_read_b32 v162, v195 offset:59520
	v_add_u32_e32 v196, 11, v186
	v_max_i32_e32 v236, 0xffffffe0, v196
	v_max_i32_e32 v196, 0, v196
	v_lshlrev_b32_e32 v196, 2, v196
	v_lshlrev_b32_e32 v236, 2, v236
	ds_read_b32 v147, v196 offset:59392
	ds_read_b32 v163, v236 offset:59520
	s_waitcnt lgkmcnt(0)
	v_add_f32_e32 v68, v68, v144
	v_add_f32_e32 v84, v84, v160
	v_add_f32_e32 v69, v69, v145
	v_add_f32_e32 v85, v85, v161
	v_add_f32_e32 v70, v70, v146
	v_add_f32_e32 v86, v86, v162
	v_add_f32_e32 v71, v71, v147
	v_add_f32_e32 v87, v87, v163
	v_add_u32_e32 v187, 16, v186
	v_max_i32_e32 v188, 0xffffffe0, v187
	v_max_i32_e32 v187, 0, v187
	v_lshlrev_b32_e32 v187, 2, v187
	v_lshlrev_b32_e32 v188, 2, v188
	ds_read_b32 v148, v187 offset:59392
	ds_read_b32 v164, v188 offset:59520
	v_add_u32_e32 v189, 17, v186
	v_max_i32_e32 v190, 0xffffffe0, v189
	v_max_i32_e32 v189, 0, v189
	v_lshlrev_b32_e32 v189, 2, v189
	v_lshlrev_b32_e32 v190, 2, v190
	ds_read_b32 v149, v189 offset:59392
	ds_read_b32 v165, v190 offset:59520
	v_add_u32_e32 v193, 18, v186
	v_max_i32_e32 v195, 0xffffffe0, v193
	v_max_i32_e32 v193, 0, v193
	v_lshlrev_b32_e32 v193, 2, v193
	v_lshlrev_b32_e32 v195, 2, v195
	ds_read_b32 v150, v193 offset:59392
	ds_read_b32 v166, v195 offset:59520
	v_add_u32_e32 v196, 19, v186
	v_max_i32_e32 v236, 0xffffffe0, v196
	v_max_i32_e32 v196, 0, v196
	v_lshlrev_b32_e32 v196, 2, v196
	v_lshlrev_b32_e32 v236, 2, v236
	ds_read_b32 v151, v196 offset:59392
	ds_read_b32 v167, v236 offset:59520
	s_waitcnt lgkmcnt(0)
	v_add_f32_e32 v72, v72, v148
	v_add_f32_e32 v88, v88, v164
	v_add_f32_e32 v73, v73, v149
	v_add_f32_e32 v89, v89, v165
	v_add_f32_e32 v74, v74, v150
	v_add_f32_e32 v90, v90, v166
	v_add_f32_e32 v75, v75, v151
	v_add_f32_e32 v91, v91, v167
	v_add_u32_e32 v187, 24, v186
	v_max_i32_e32 v188, 0xffffffe0, v187
	v_max_i32_e32 v187, 0, v187
	v_lshlrev_b32_e32 v187, 2, v187
	v_lshlrev_b32_e32 v188, 2, v188
	ds_read_b32 v152, v187 offset:59392
	ds_read_b32 v168, v188 offset:59520
	v_add_u32_e32 v189, 25, v186
	v_max_i32_e32 v190, 0xffffffe0, v189
	v_max_i32_e32 v189, 0, v189
	v_lshlrev_b32_e32 v189, 2, v189
	v_lshlrev_b32_e32 v190, 2, v190
	ds_read_b32 v153, v189 offset:59392
	ds_read_b32 v169, v190 offset:59520
	v_add_u32_e32 v193, 26, v186
	v_max_i32_e32 v195, 0xffffffe0, v193
	v_max_i32_e32 v193, 0, v193
	v_lshlrev_b32_e32 v193, 2, v193
	v_lshlrev_b32_e32 v195, 2, v195
	ds_read_b32 v154, v193 offset:59392
	ds_read_b32 v170, v195 offset:59520
	v_add_u32_e32 v196, 27, v186
	v_max_i32_e32 v236, 0xffffffe0, v196
	v_max_i32_e32 v196, 0, v196
	v_lshlrev_b32_e32 v196, 2, v196
	v_lshlrev_b32_e32 v236, 2, v236
	ds_read_b32 v155, v196 offset:59392
	ds_read_b32 v171, v236 offset:59520
	s_waitcnt lgkmcnt(0)
	v_add_f32_e32 v76, v76, v152
	v_add_f32_e32 v92, v92, v168
	v_add_f32_e32 v77, v77, v153
	v_add_f32_e32 v93, v93, v169
	v_add_f32_e32 v78, v78, v154
	v_add_f32_e32 v94, v94, v170
	v_add_f32_e32 v79, v79, v155
	v_add_f32_e32 v95, v95, v171

; template <int DQK, int KA8, int DV, bool BIAS, bool JOINT>
; DI void attn_core(LAS unsigned char* lds, const bf16_t* Qrow, const bf16_t* KpA, int ldkA, const bf16_t* KpB, int ldkB, const bf16_t* Vp, int ldv,
;                   int qb, int wid, int lane, const float* qng  , f32x16 (&O)[DV / 32]) {
;     ...
;             if (mnz) {
; #pragma unroll
;                 for (int i = 0; i < 16; ++i) { S0[i] -= m; S1[i] -= m; }
;             }
;             float mx = fmaxf(S0[0], S1[0]);
; #pragma unroll
;             for (int i = 1; i < 16; ++i) mx = fmaxf(mx, fmaxf(S0[i], S1[i]));
;             mx = fmaxf(mx, __shfl_xor(mx, 32));
;             if (__any(mx > 64.f || (kt == 0 && mx < -64.f))) {
;                 const float dm = (mx > 64.f || (kt == 0 && mx < -64.f)) ? mx : 0.f, alpha = __builtin_amdgcn_exp2f(-dm); m += dm; mnz = true;
;                 l *= alpha;
; #pragma unroll
;                 for (int dt = 0; dt < DV / 32; ++dt) O[dt] *= alpha;
; #pragma unroll
;                 for (int i = 0; i < 16; ++i) { S0[i] -= dm; S1[i] -= dm; }
;             }
.Laa_y1_nosubm:
	v_max3_f32 v186, v64, v65, v66
	v_max3_f32 v189, v67, v68, v69
	v_max3_f32 v190, v70, v71, v72
	v_max3_f32 v193, v73, v74, v75
	v_max3_f32 v186, v186, v76, v77
	v_max3_f32 v189, v189, v78, v79
	v_max3_f32 v190, v190, v80, v81
	v_max3_f32 v193, v193, v82, v83
	v_max3_f32 v186, v186, v84, v85
	v_max3_f32 v189, v189, v86, v87
	v_max3_f32 v190, v190, v88, v89
	v_max3_f32 v193, v193, v90, v91
	v_max3_f32 v186, v186, v92, v93
	v_max3_f32 v189, v189, v94, v95
	v_max3_f32 v186, v186, v189, v190
	v_max_f32_e32 v186, v186, v193
	v_mov_b32_e32 v187, v186
	v_mov_b32_e32 v188, v186
	s_nop 1
	v_permlane32_swap_b32_e32 v187, v188
	s_nop 1
	v_max_f32_e32 v186, v187, v188
	v_cmp_lt_f32_e32 vcc, 0x42800000, v186
	s_cmp_lg_u64 vcc, 0
	s_cbranch_scc0 .Laa_y1_noresc
	s_nop 3
	v_cndmask_b32_e32 v189, 0, v186, vcc
	v_exp_f32_e64 v190, -v189
	v_add_f32_e32 v183, v183, v189
	s_mov_b32 s40, 1
	v_mul_f32_e32 v184, v184, v190
	v_mul_f32_e32 v0, v0, v190
	v_mul_f32_e32 v1, v1, v190
	v_mul_f32_e32 v2, v2, v190
	v_mul_f32_e32 v3, v3, v190
	v_mul_f32_e32 v4, v4, v190
	v_mul_f32_e32 v5, v5, v190
	v_mul_f32_e32 v6, v6, v190
	v_mul_f32_e32 v7, v7, v190
	v_mul_f32_e32 v8, v8, v190
	v_mul_f32_e32 v9, v9, v190
	v_mul_f32_e32 v10, v10, v190
	v_mul_f32_e32 v11, v11, v190
	v_mul_f32_e32 v12, v12, v190
	v_mul_f32_e32 v13, v13, v190
	v_mul_f32_e32 v14, v14, v190
	v_mul_f32_e32 v15, v15, v190
	v_mul_f32_e32 v16, v16, v190
	v_mul_f32_e32 v17, v17, v190
	v_mul_f32_e32 v18, v18, v190
	v_mul_f32_e32 v19, v19, v190
	v_mul_f32_e32 v20, v20, v190
	v_mul_f32_e32 v21, v21, v190
	v_mul_f32_e32 v22, v22, v190
	v_mul_f32_e32 v23, v23, v190
	v_mul_f32_e32 v24, v24, v190
	v_mul_f32_e32 v25, v25, v190
	v_mul_f32_e32 v26, v26, v190
	v_mul_f32_e32 v27, v27, v190
	v_mul_f32_e32 v28, v28, v190
	v_mul_f32_e32 v29, v29, v190
	v_mul_f32_e32 v30, v30, v190
	v_mul_f32_e32 v31, v31, v190
	v_mul_f32_e32 v32, v32, v190
	v_mul_f32_e32 v33, v33, v190
	v_mul_f32_e32 v34, v34, v190
	v_mul_f32_e32 v35, v35, v190
	v_mul_f32_e32 v36, v36, v190
	v_mul_f32_e32 v37, v37, v190
	v_mul_f32_e32 v38, v38, v190
	v_mul_f32_e32 v39, v39, v190
	v_mul_f32_e32 v40, v40, v190
	v_mul_f32_e32 v41, v41, v190
	v_mul_f32_e32 v42, v42, v190
	v_mul_f32_e32 v43, v43, v190
	v_mul_f32_e32 v44, v44, v190
	v_mul_f32_e32 v45, v45, v190
	v_mul_f32_e32 v46, v46, v190
	v_mul_f32_e32 v47, v47, v190
	v_mul_f32_e32 v48, v48, v190
	v_mul_f32_e32 v49, v49, v190
	v_mul_f32_e32 v50, v50, v190
	v_mul_f32_e32 v51, v51, v190
	v_mul_f32_e32 v52, v52, v190
	v_mul_f32_e32 v53, v53, v190
	v_mul_f32_e32 v54, v54, v190
	v_mul_f32_e32 v55, v55, v190
	v_mul_f32_e32 v56, v56, v190
	v_mul_f32_e32 v57, v57, v190
	v_mul_f32_e32 v58, v58, v190
	v_mul_f32_e32 v59, v59, v190
	v_mul_f32_e32 v60, v60, v190
	v_mul_f32_e32 v61, v61, v190
	v_mul_f32_e32 v62, v62, v190
	v_mul_f32_e32 v63, v63, v190
	v_sub_f32_e32 v64, v64, v189
	v_sub_f32_e32 v65, v65, v189
	v_sub_f32_e32 v66, v66, v189
	v_sub_f32_e32 v67, v67, v189
	v_sub_f32_e32 v68, v68, v189
	v_sub_f32_e32 v69, v69, v189
	v_sub_f32_e32 v70, v70, v189
	v_sub_f32_e32 v71, v71, v189
	v_sub_f32_e32 v72, v72, v189
	v_sub_f32_e32 v73, v73, v189
	v_sub_f32_e32 v74, v74, v189
	v_sub_f32_e32 v75, v75, v189
	v_sub_f32_e32 v76, v76, v189
	v_sub_f32_e32 v77, v77, v189
	v_sub_f32_e32 v78, v78, v189
	v_sub_f32_e32 v79, v79, v189
	v_sub_f32_e32 v80, v80, v189
	v_sub_f32_e32 v81, v81, v189
	v_sub_f32_e32 v82, v82, v189
	v_sub_f32_e32 v83, v83, v189
	v_sub_f32_e32 v84, v84, v189
	v_sub_f32_e32 v85, v85, v189
	v_sub_f32_e32 v86, v86, v189
	v_sub_f32_e32 v87, v87, v189
	v_sub_f32_e32 v88, v88, v189
	v_sub_f32_e32 v89, v89, v189
	v_sub_f32_e32 v90, v90, v189
	v_sub_f32_e32 v91, v91, v189
	v_sub_f32_e32 v92, v92, v189
	v_sub_f32_e32 v93, v93, v189
	v_sub_f32_e32 v94, v94, v189
	v_sub_f32_e32 v95, v95, v189

; #define LAS __attribute__((address_space(3)))
; DI unsigned pk2(float a, float b) { f32x2 v = {a, b}; bf16v2_t r = __builtin_convertvector(v, bf16v2_t); return __builtin_bit_cast(unsigned, r); }
; DI f32x16 mfma32(bf16x8 a, bf16x8 b, f32x16 c) { return __builtin_amdgcn_mfma_f32_32x32x16_bf16(a, b, c, 0, 0, 0); }
; DI s16x4 trread(LAS unsigned char* p) { return __builtin_amdgcn_ds_read_tr16_b64_v4i16((LAS s16x4*)p); }
; DI bf16x8 cat4(s16x4 lo, s16x4 hi) { return __builtin_shufflevector(lo, hi, 0, 1, 2, 3, 4, 5, 6, 7); }
; template <int DQK, int KA8, int DV, bool BIAS, bool JOINT>
; DI void attn_core(LAS unsigned char* lds, const bf16_t* Qrow, const bf16_t* KpA, int ldkA, const bf16_t* KpB, int ldkB, const bf16_t* Vp, int ldv,
;                   int qb, int wid, int lane, const float* qng  , f32x16 (&O)[DV / 32]) {
;     ...
;             for (int half = 0; half < 2; ++half)
; #pragma unroll
;                 for (int s = 0; s < 2; ++s) {
;                     const f32x16& S = half ? S1 : S0;
;                     u32x4 pw; pw.x = pk2(S[8 * s], S[8 * s + 1]); pw.y = pk2(S[8 * s + 2], S[8 * s + 3]); pw.z = pk2(S[8 * s + 4], S[8 * s + 5]); pw.w = pk2(S[8 * s + 6], S[8 * s + 7]);
;                     const bf16x8 pf = __builtin_bit_cast(bf16x8, pw);
;                     LAS unsigned char* vr = vb + vtr + (32 * half + 16 * s) * VROW;
; #pragma unroll
;                     for (int dt = 0; dt < DV / 32; ++dt) {
;                         const bf16x8 vf = cat4(trread(vr + 64 * dt), trread(vr + 8 * VROW + 64 * dt));
;                         O[dt] = mfma32(vf, pf, O[dt]);
;                     }
;                 }
.Laa_y1_end:
	s_barrier
	s_add_i32 s24, s24, 2
	s_cmp_lt_u32 s24, s17
	s_cbranch_scc1 .Laa_loop
	s_add_i32 s58, s25, 1
	s_cmp_ge_u32 s58, s17
	s_cbranch_scc0 .Laa_nofpv
	ds_read_b64_tr_b16 v[140:141], v173 offset:38912
	ds_read_b64_tr_b16 v[142:143], v173 offset:41472
	ds_read_b64_tr_b16 v[144:145], v173 offset:38976
	ds_read_b64_tr_b16 v[146:147], v173 offset:41536
	ds_read_b64_tr_b16 v[148:149], v173 offset:39040
	ds_read_b64_tr_b16 v[150:151], v173 offset:41600
	ds_read_b64_tr_b16 v[152:153], v173 offset:39104
	ds_read_b64_tr_b16 v[154:155], v173 offset:41664
	ds_read_b64_tr_b16 v[156:157], v173 offset:44032
	ds_read_b64_tr_b16 v[158:159], v173 offset:46592
	ds_read_b64_tr_b16 v[160:161], v173 offset:44096
	ds_read_b64_tr_b16 v[162:163], v173 offset:46656
	s_waitcnt lgkmcnt(10)
	v_mfma_f32_32x32x16_bf16 v[0:15], v[140:143], v[96:99], v[0:15]
	ds_read_b64_tr_b16 v[164:165], v173 offset:44160
	ds_read_b64_tr_b16 v[166:167], v173 offset:46720
	s_waitcnt lgkmcnt(10)
	v_mfma_f32_32x32x16_bf16 v[16:31], v[144:147], v[96:99], v[16:31]
	ds_read_b64_tr_b16 v[168:169], v173 offset:44224
	ds_read_b64_tr_b16 v[170:171], v173 offset:46784
	s_waitcnt lgkmcnt(10)
	v_mfma_f32_32x32x16_bf16 v[32:47], v[148:151], v[96:99], v[32:47]
	ds_read_b64_tr_b16 v[140:141], v173 offset:49152
	ds_read_b64_tr_b16 v[142:143], v173 offset:51712
	s_waitcnt lgkmcnt(10)
	v_mfma_f32_32x32x16_bf16 v[48:63], v[152:155], v[96:99], v[48:63]
	ds_read_b64_tr_b16 v[144:145], v173 offset:49216
	ds_read_b64_tr_b16 v[146:147], v173 offset:51776
	s_waitcnt lgkmcnt(10)
	v_mfma_f32_32x32x16_bf16 v[0:15], v[156:159], v[100:103], v[0:15]
	ds_read_b64_tr_b16 v[148:149], v173 offset:49280
	ds_read_b64_tr_b16 v[150:151], v173 offset:51840
	s_waitcnt lgkmcnt(10)
	v_mfma_f32_32x32x16_bf16 v[16:31], v[160:163], v[100:103], v[16:31]
	ds_read_b64_tr_b16 v[152:153], v173 offset:49344
	ds_read_b64_tr_b16 v[154:155], v173 offset:51904
	s_waitcnt lgkmcnt(10)
	v_mfma_f32_32x32x16_bf16 v[32:47], v[164:167], v[100:103], v[32:47]
	ds_read_b64_tr_b16 v[156:157], v173 offset:54272
	ds_read_b64_tr_b16 v[158:159], v173 offset:56832
	s_waitcnt lgkmcnt(10)
	v_mfma_f32_32x32x16_bf16 v[48:63], v[168:171], v[100:103], v[48:63]
	ds_read_b64_tr_b16 v[160:161], v173 offset:54336
	ds_read_b64_tr_b16 v[162:163], v173 offset:56896
	s_waitcnt lgkmcnt(10)
	v_mfma_f32_32x32x16_bf16 v[0:15], v[140:143], v[104:107], v[0:15]
	ds_read_b64_tr_b16 v[164:165], v173 offset:54400
	ds_read_b64_tr_b16 v[166:167], v173 offset:56960
	s_waitcnt lgkmcnt(10)
	v_mfma_f32_32x32x16_bf16 v[16:31], v[144:147], v[104:107], v[16:31]
	ds_read_b64_tr_b16 v[168:169], v173 offset:54464
	ds_read_b64_tr_b16 v[170:171], v173 offset:57024
	s_waitcnt lgkmcnt(10)
	v_mfma_f32_32x32x16_bf16 v[32:47], v[148:151], v[104:107], v[32:47]
	s_waitcnt lgkmcnt(8)
	v_mfma_f32_32x32x16_bf16 v[48:63], v[152:155], v[104:107], v[48:63]
	s_waitcnt lgkmcnt(6)
	v_mfma_f32_32x32x16_bf16 v[0:15], v[156:159], v[108:111], v[0:15]
	s_waitcnt lgkmcnt(4)
	v_mfma_f32_32x32x16_bf16 v[16:31], v[160:163], v[108:111], v[16:31]
	s_waitcnt lgkmcnt(2)
	v_mfma_f32_32x32x16_bf16 v[32:47], v[164:167], v[108:111], v[32:47]
	s_waitcnt lgkmcnt(0)
	v_mfma_f32_32x32x16_bf16 v[48:63], v[168:171], v[108:111], v[48:63]
